# attention loops: ALiBi score init rewritten as v_add_f32 + v_fma_f32 with |d| source modifier (bit-identical ops) replacing v_pk_add / 2x v_and / v_pk_fma: fewer issue cycles in an issue-bound loop; o
# speedup vs baseline: 1.0675x; 1.0053x over previous
.LBB0_226:
	v_cvt_f32_i32_e32 v162, v127
	s_lshl_b32 s86, s33, 15
	v_or_b32_e32 v102, s86, v200
	s_waitcnt lgkmcnt(0)
	v_add_f32_e32 v67, 1.0, v162
	v_add_f32_e32 v68, s12, v162
	v_add_f32_e32 v69, s13, v162
	v_add_f32_e32 v70, s16, v162
	v_add_f32_e32 v71, s17, v162
	v_add_f32_e32 v72, s18, v162
	v_add_f32_e32 v73, s19, v162
	v_add_f32_e32 v74, s20, v162
	v_add_f32_e32 v75, s21, v162
	v_add_f32_e32 v76, s22, v162
	v_add_f32_e32 v77, s23, v162
	v_add_f32_e32 v78, s26, v162
	v_add_f32_e32 v79, s27, v162
	v_add_f32_e32 v80, s28, v162
	v_add_f32_e32 v81, s29, v162
	s_barrier
	v_add_u32_e32 v129, v102, v202
	v_fma_f32 v66, v106, |v162|, v146
	v_fma_f32 v67, v106, |v67|, v146
	v_fma_f32 v68, v106, |v68|, v146
	v_fma_f32 v69, v106, |v69|, v146
	v_fma_f32 v70, v106, |v70|, v146
	v_fma_f32 v71, v106, |v71|, v146
	v_fma_f32 v72, v106, |v72|, v146
	v_fma_f32 v73, v106, |v73|, v146
	v_fma_f32 v74, v106, |v74|, v146
	v_fma_f32 v75, v106, |v75|, v146
	v_fma_f32 v76, v106, |v76|, v146
	v_fma_f32 v77, v106, |v77|, v146
	v_fma_f32 v78, v106, |v78|, v146
	v_fma_f32 v79, v106, |v79|, v146
	v_fma_f32 v80, v106, |v80|, v146
	v_fma_f32 v81, v106, |v81|, v146
	ds_read_b128 v[98:101], v129
	v_add_u32_e32 v151, v102, v203
	s_waitcnt vmcnt(3) lgkmcnt(0)
	v_mfma_f32_32x32x16_bf16 v[66:81], v[98:101], v[82:85], v[66:81]
	ds_read_b128 v[98:101], v151
	v_add_u32_e32 v157, v102, v204
	v_add_u32_e32 v161, v102, v205
	s_add_i32 s6, s33, 1
	v_add_u32_e32 v128, 1, v128
	s_cmp_lg_u32 s33, 2
	v_cmp_ge_i32_e32 vcc, v128, v155
	s_waitcnt vmcnt(2) lgkmcnt(0)
	v_mfma_f32_32x32x16_bf16 v[66:81], v[98:101], v[86:89], v[66:81]
	ds_read_b128 v[98:101], v157
	s_cselect_b32 s33, s6, 0
	v_add_u32_e32 v127, 64, v127
	s_or_b64 s[84:85], vcc, s[84:85]
	s_waitcnt vmcnt(1) lgkmcnt(0)
	v_mfma_f32_32x32x16_bf16 v[66:81], v[98:101], v[90:93], v[66:81]
	ds_read_b128 v[98:101], v161
	s_waitcnt vmcnt(0) lgkmcnt(0)
	v_mfma_f32_32x32x16_bf16 v[66:81], v[98:101], v[94:97], v[66:81]
	s_nop 11
	v_exp_f32_e32 v66, v66
	v_exp_f32_e32 v166, v67
	v_exp_f32_e32 v168, v68
	v_exp_f32_e32 v170, v69
	v_add_f32_e32 v132, 0, v66
	v_exp_f32_e32 v188, v78
	v_exp_f32_e32 v212, v79
	v_exp_f32_e32 v214, v80
	v_exp_f32_e32 v216, v81
	v_cvt_pk_bf16_f32 v98, v66, v166
	v_exp_f32_e32 v172, v70
	v_exp_f32_e32 v174, v71
	v_exp_f32_e32 v176, v72
	v_exp_f32_e32 v178, v73
	v_exp_f32_e32 v180, v74
	v_exp_f32_e32 v182, v75
	v_exp_f32_e32 v184, v76
	v_exp_f32_e32 v186, v77
	v_add_f32_e32 v66, s74, v162
	v_add_f32_e32 v67, s75, v162
	v_add_f32_e32 v68, s64, v162
	v_add_f32_e32 v69, s65, v162
	v_add_f32_e32 v70, s58, v162
	v_add_f32_e32 v71, s59, v162
	v_add_f32_e32 v72, s56, v162
	v_add_f32_e32 v73, s57, v162
	v_add_f32_e32 v74, s54, v162
	v_add_f32_e32 v75, s55, v162
	v_add_f32_e32 v76, s48, v162
	v_add_f32_e32 v77, s49, v162
	v_add_f32_e32 v78, s34, v162
	v_add_f32_e32 v79, s35, v162
	v_add_f32_e32 v80, s30, v162
	v_add_f32_e32 v81, s31, v162
	v_fma_f32 v66, v106, |v66|, v146
	v_fma_f32 v67, v106, |v67|, v146
	v_fma_f32 v68, v106, |v68|, v146
	v_fma_f32 v69, v106, |v69|, v146
	v_fma_f32 v70, v106, |v70|, v146
	v_fma_f32 v71, v106, |v71|, v146
	v_fma_f32 v72, v106, |v72|, v146
	v_fma_f32 v73, v106, |v73|, v146
	v_fma_f32 v74, v106, |v74|, v146
	v_fma_f32 v75, v106, |v75|, v146
	v_fma_f32 v76, v106, |v76|, v146
	v_fma_f32 v77, v106, |v77|, v146
	v_fma_f32 v78, v106, |v78|, v146
	v_fma_f32 v79, v106, |v79|, v146
	v_fma_f32 v80, v106, |v80|, v146
	v_fma_f32 v81, v106, |v81|, v146
	ds_read_b128 v[162:165], v129 offset:8192
	v_cvt_pk_bf16_f32 v99, v168, v170
	v_cvt_pk_bf16_f32 v100, v172, v174
	s_waitcnt lgkmcnt(0)
	v_mfma_f32_32x32x16_bf16 v[66:81], v[162:165], v[82:85], v[66:81]
	ds_read_b128 v[162:165], v151 offset:8192
	v_cvt_pk_bf16_f32 v101, v176, v178
	v_cvt_pk_bf16_f32 v102, v180, v182
	v_cvt_pk_bf16_f32 v103, v184, v186
	v_cvt_pk_bf16_f32 v104, v188, v212
	v_cvt_pk_bf16_f32 v105, v214, v216
	s_waitcnt lgkmcnt(0)
	v_mfma_f32_32x32x16_bf16 v[66:81], v[162:165], v[86:89], v[66:81]
	ds_read_b128 v[162:165], v157 offset:8192
	s_waitcnt lgkmcnt(0)
	v_mfma_f32_32x32x16_bf16 v[66:81], v[162:165], v[90:93], v[66:81]
	ds_read_b128 v[162:165], v161 offset:8192
	s_waitcnt lgkmcnt(0)
	s_barrier
	s_waitcnt lgkmcnt(0)
	v_mfma_f32_32x32x16_bf16 v[66:81], v[162:165], v[94:97], v[66:81]
	s_nop 11
	v_exp_f32_e32 v217, v80
	v_or_b32_e32 v80, s86, v193
	v_exp_f32_e32 v161, v81
	v_add_u32_e32 v81, v80, v195
	v_exp_f32_e32 v183, v74
	v_exp_f32_e32 v185, v75
	v_exp_f32_e32 v187, v76
	v_exp_f32_e32 v189, v77
	ds_read_b128 v[74:77], v81 offset:16384
	v_add_u32_e32 v129, v80, v196
	s_waitcnt lgkmcnt(0)
	v_mfma_f32_32x32x16_bf16 v[50:65], v[74:77], v[98:101], v[50:65]
	ds_read_b128 v[74:77], v129 offset:16384
	v_exp_f32_e32 v167, v66
	v_exp_f32_e32 v169, v67
	v_exp_f32_e32 v171, v68
	v_exp_f32_e32 v173, v69
	v_pk_add_f32 v[66:67], v[166:167], v[132:133]
	v_exp_f32_e32 v175, v70
	s_waitcnt lgkmcnt(0)
	v_mfma_f32_32x32x16_bf16 v[50:65], v[74:77], v[102:105], v[50:65]
	ds_read_b128 v[74:77], v81 offset:20480
	v_add_f32_e64 v66, v168, v66
	v_add_f32_e64 v67, v169, v67
	v_exp_f32_e32 v177, v71
	v_pk_add_f32 v[66:67], v[170:171], v[66:67]
	v_exp_f32_e32 v179, v72
	v_pk_add_f32 v[66:67], v[172:173], v[66:67]
	v_exp_f32_e32 v181, v73
	s_waitcnt lgkmcnt(0)
	v_mfma_f32_32x32x16_bf16 v[34:49], v[74:77], v[98:101], v[34:49]
	ds_read_b128 v[74:77], v129 offset:20480
	v_add_f32_e64 v66, v174, v66
	v_add_f32_e64 v67, v175, v67
	v_exp_f32_e32 v213, v78
	v_pk_add_f32 v[66:67], v[176:177], v[66:67]
	v_exp_f32_e32 v215, v79
	v_pk_add_f32 v[66:67], v[178:179], v[66:67]
	v_cvt_pk_bf16_f32 v68, v175, v177
	s_waitcnt lgkmcnt(0)
	v_mfma_f32_32x32x16_bf16 v[34:49], v[74:77], v[102:105], v[34:49]
	ds_read_b128 v[74:77], v81 offset:24576
	v_add_f32_e64 v66, v180, v66
	v_add_f32_e64 v67, v181, v67
	v_cvt_pk_bf16_f32 v69, v179, v181
	v_add_f32_e64 v66, v182, v66
	v_add_f32_e64 v67, v183, v67
	v_cvt_pk_bf16_f32 v70, v183, v185
	v_pk_add_f32 v[66:67], v[184:185], v[66:67]
	v_cvt_pk_bf16_f32 v71, v187, v189
	s_waitcnt lgkmcnt(0)
	v_mfma_f32_32x32x16_bf16 v[18:33], v[74:77], v[98:101], v[18:33]
	ds_read_b128 v[74:77], v129 offset:24576
	v_add_f32_e64 v66, v186, v66
	v_add_f32_e64 v67, v187, v67
	v_cvt_pk_bf16_f32 v72, v213, v215
	v_add_f32_e64 v66, v188, v66
	v_add_f32_e64 v67, v189, v67
	v_cvt_pk_bf16_f32 v73, v217, v161
	v_pk_add_f32 v[66:67], v[212:213], v[66:67]
	s_waitcnt lgkmcnt(0)
	v_mfma_f32_32x32x16_bf16 v[18:33], v[74:77], v[102:105], v[18:33]
	ds_read_b128 v[74:77], v81 offset:28672
	v_add_u32_e32 v81, v80, v197
	v_add_f32_e64 v66, v214, v66
	v_add_f32_e64 v67, v215, v67
	v_add_u32_e32 v80, v80, v198
	v_pk_add_f32 v[66:67], v[216:217], v[66:67]
	s_nop 0
	v_pk_add_f32 v[78:79], v[160:161], v[66:67]
	s_waitcnt lgkmcnt(0)
	v_mfma_f32_32x32x16_bf16 v[2:17], v[74:77], v[98:101], v[2:17]
	ds_read_b128 v[74:77], v129 offset:28672
	v_cvt_pk_bf16_f32 v66, v167, v169
	v_cvt_pk_bf16_f32 v67, v171, v173
	v_add_f32_e32 v160, v78, v79
	s_waitcnt lgkmcnt(0)
	v_mfma_f32_32x32x16_bf16 v[2:17], v[74:77], v[102:105], v[2:17]
	ds_read_b128 v[74:77], v81 offset:16384
	s_waitcnt lgkmcnt(0)
	v_mfma_f32_32x32x16_bf16 v[50:65], v[74:77], v[66:69], v[50:65]
	ds_read_b128 v[74:77], v80 offset:16384
	s_waitcnt lgkmcnt(0)
	v_mfma_f32_32x32x16_bf16 v[50:65], v[74:77], v[70:73], v[50:65]
	ds_read_b128 v[74:77], v81 offset:20480
	s_waitcnt lgkmcnt(0)
	v_mfma_f32_32x32x16_bf16 v[34:49], v[74:77], v[66:69], v[34:49]
	ds_read_b128 v[74:77], v80 offset:20480
	s_waitcnt lgkmcnt(0)
	v_mfma_f32_32x32x16_bf16 v[34:49], v[74:77], v[70:73], v[34:49]
	ds_read_b128 v[74:77], v81 offset:24576
	s_waitcnt lgkmcnt(0)
	v_mfma_f32_32x32x16_bf16 v[18:33], v[74:77], v[66:69], v[18:33]
	ds_read_b128 v[74:77], v80 offset:24576
	s_waitcnt lgkmcnt(0)
	v_mfma_f32_32x32x16_bf16 v[18:33], v[74:77], v[70:73], v[18:33]
	ds_read_b128 v[74:77], v81 offset:28672
	s_waitcnt lgkmcnt(0)
	v_mfma_f32_32x32x16_bf16 v[2:17], v[74:77], v[66:69], v[2:17]
	ds_read_b128 v[66:69], v80 offset:28672
	s_waitcnt lgkmcnt(0)
	v_mfma_f32_32x32x16_bf16 v[2:17], v[66:69], v[70:73], v[2:17]
	s_andn2_b64 exec, exec, s[84:85]
	s_cbranch_execnz .LBB0_226
	s_or_b64 exec, exec, s[84:85]

.LBB0_232:
	s_or_b64 exec, exec, s[86:87]
	v_add_u32_e32 v66, v151, v66
	v_cvt_f32_i32_e32 v212, v66
	s_and_b64 s[6:7], exec, vcc
	s_or_b64 s[84:85], s[6:7], s[84:85]
	s_lshl_b32 s86, s90, 15
	v_or_b32_e32 v102, s86, v200
	v_add_f32_e32 v67, 1.0, v212
	v_add_f32_e32 v68, s12, v212
	v_add_f32_e32 v69, s13, v212
	v_add_f32_e32 v70, s16, v212
	v_add_f32_e32 v71, s17, v212
	v_add_f32_e32 v72, s18, v212
	v_add_f32_e32 v73, s19, v212
	v_add_f32_e32 v74, s20, v212
	v_add_f32_e32 v75, s21, v212
	v_add_f32_e32 v76, s22, v212
	v_add_f32_e32 v77, s23, v212
	v_add_f32_e32 v78, s26, v212
	v_add_f32_e32 v79, s27, v212
	v_add_f32_e32 v80, s28, v212
	v_add_f32_e32 v81, s29, v212
	v_add_u32_e32 v127, v102, v202
	v_fma_f32 v66, v110, |v212|, v146
	v_fma_f32 v67, v110, |v67|, v146
	v_fma_f32 v68, v110, |v68|, v146
	v_fma_f32 v69, v110, |v69|, v146
	v_fma_f32 v70, v110, |v70|, v146
	v_fma_f32 v71, v110, |v71|, v146
	v_fma_f32 v72, v110, |v72|, v146
	v_fma_f32 v73, v110, |v73|, v146
	v_fma_f32 v74, v110, |v74|, v146
	v_fma_f32 v75, v110, |v75|, v146
	v_fma_f32 v76, v110, |v76|, v146
	v_fma_f32 v77, v110, |v77|, v146
	v_fma_f32 v78, v110, |v78|, v146
	v_fma_f32 v79, v110, |v79|, v146
	v_fma_f32 v80, v110, |v80|, v146
	v_fma_f32 v81, v110, |v81|, v146
	ds_read_b128 v[98:101], v127
	v_add_u32_e32 v129, v102, v203
	s_waitcnt lgkmcnt(0)
	v_mfma_f32_32x32x16_bf16 v[66:81], v[98:101], v[82:85], v[66:81]
	ds_read_b128 v[98:101], v129
	v_add_u32_e32 v157, v102, v204
	v_add_u32_e32 v161, v102, v205
	v_add_u32_e32 v141, 1, v141
	s_mov_b32 s90, s33
	s_waitcnt lgkmcnt(0)
	v_mfma_f32_32x32x16_bf16 v[66:81], v[98:101], v[86:89], v[66:81]
	ds_read_b128 v[98:101], v157
	s_waitcnt lgkmcnt(0)
	v_mfma_f32_32x32x16_bf16 v[66:81], v[98:101], v[90:93], v[66:81]
	ds_read_b128 v[98:101], v161
	s_waitcnt lgkmcnt(0)
	v_mfma_f32_32x32x16_bf16 v[66:81], v[98:101], v[94:97], v[66:81]
	s_nop 11
	v_exp_f32_e32 v66, v66
	v_exp_f32_e32 v128, v67
	v_exp_f32_e32 v164, v68
	v_exp_f32_e32 v162, v69
	v_add_f32_e32 v132, 0, v66
	v_exp_f32_e32 v184, v78
	v_exp_f32_e32 v182, v79
	v_exp_f32_e32 v188, v80
	v_exp_f32_e32 v186, v81
	v_cvt_pk_bf16_f32 v102, v66, v128
	v_exp_f32_e32 v168, v70
	v_exp_f32_e32 v166, v71
	v_exp_f32_e32 v172, v72
	v_exp_f32_e32 v170, v73
	v_exp_f32_e32 v176, v74
	v_exp_f32_e32 v174, v75
	v_exp_f32_e32 v180, v76
	v_exp_f32_e32 v178, v77
	v_add_f32_e32 v66, s74, v212
	v_add_f32_e32 v67, s75, v212
	v_add_f32_e32 v68, s64, v212
	v_add_f32_e32 v69, s65, v212
	v_add_f32_e32 v70, s58, v212
	v_add_f32_e32 v71, s59, v212
	v_add_f32_e32 v72, s56, v212
	v_add_f32_e32 v73, s57, v212
	v_add_f32_e32 v74, s54, v212
	v_add_f32_e32 v75, s55, v212
	v_add_f32_e32 v76, s48, v212
	v_add_f32_e32 v77, s49, v212
	v_add_f32_e32 v78, s34, v212
	v_add_f32_e32 v79, s35, v212
	v_add_f32_e32 v80, s30, v212
	v_add_f32_e32 v81, s31, v212
	v_fma_f32 v66, v110, |v66|, v146
	v_fma_f32 v67, v110, |v67|, v146
	v_fma_f32 v68, v110, |v68|, v146
	v_fma_f32 v69, v110, |v69|, v146
	v_fma_f32 v70, v110, |v70|, v146
	v_fma_f32 v71, v110, |v71|, v146
	v_fma_f32 v72, v110, |v72|, v146
	v_fma_f32 v73, v110, |v73|, v146
	v_fma_f32 v74, v110, |v74|, v146
	v_fma_f32 v75, v110, |v75|, v146
	v_fma_f32 v76, v110, |v76|, v146
	v_fma_f32 v77, v110, |v77|, v146
	v_fma_f32 v78, v110, |v78|, v146
	v_fma_f32 v79, v110, |v79|, v146
	v_fma_f32 v80, v110, |v80|, v146
	v_fma_f32 v81, v110, |v81|, v146
	ds_read_b128 v[212:215], v127 offset:8192
	v_cvt_pk_bf16_f32 v103, v164, v162
	v_cvt_pk_bf16_f32 v104, v168, v166
	s_waitcnt lgkmcnt(0)
	v_mfma_f32_32x32x16_bf16 v[66:81], v[212:215], v[82:85], v[66:81]
	ds_read_b128 v[212:215], v129 offset:8192
	v_cvt_pk_bf16_f32 v105, v172, v170
	v_cvt_pk_bf16_f32 v98, v176, v174
	v_cvt_pk_bf16_f32 v99, v180, v178
	v_cvt_pk_bf16_f32 v100, v184, v182
	v_cvt_pk_bf16_f32 v101, v188, v186
	s_waitcnt lgkmcnt(0)
	v_mfma_f32_32x32x16_bf16 v[66:81], v[212:215], v[86:89], v[66:81]
	ds_read_b128 v[212:215], v157 offset:8192
	s_waitcnt lgkmcnt(0)
	v_mfma_f32_32x32x16_bf16 v[66:81], v[212:215], v[90:93], v[66:81]
	ds_read_b128 v[212:215], v161 offset:8192
	s_waitcnt lgkmcnt(0)
	s_barrier
	s_waitcnt lgkmcnt(0)
	v_mfma_f32_32x32x16_bf16 v[66:81], v[212:215], v[94:97], v[66:81]
	s_nop 11
	v_exp_f32_e32 v187, v80
	v_or_b32_e32 v80, s86, v193
	v_exp_f32_e32 v161, v81
	v_add_u32_e32 v81, v80, v195
	v_exp_f32_e32 v179, v76
	v_exp_f32_e32 v185, v77
	v_exp_f32_e32 v183, v78
	v_exp_f32_e32 v189, v79
	ds_read_b128 v[76:79], v81 offset:16384
	v_add_u32_e32 v127, v80, v196
	s_waitcnt lgkmcnt(0)
	v_mfma_f32_32x32x16_bf16 v[50:65], v[76:79], v[102:105], v[50:65]
	ds_read_b128 v[76:79], v127 offset:16384
	v_exp_f32_e32 v129, v66
	v_exp_f32_e32 v165, v67
	v_exp_f32_e32 v163, v68
	v_exp_f32_e32 v169, v69
	v_pk_add_f32 v[66:67], v[128:129], v[132:133]
	v_exp_f32_e32 v167, v70
	s_waitcnt lgkmcnt(0)
	v_mfma_f32_32x32x16_bf16 v[50:65], v[76:79], v[98:101], v[50:65]
	ds_read_b128 v[76:79], v81 offset:20480
	v_add_f32_e64 v66, v164, v66
	v_add_f32_e64 v67, v165, v67
	v_exp_f32_e32 v173, v71
	v_pk_add_f32 v[66:67], v[162:163], v[66:67]
	v_exp_f32_e32 v171, v72
	v_exp_f32_e32 v177, v73
	v_pk_add_f32 v[66:67], v[168:169], v[66:67]
	s_waitcnt lgkmcnt(0)
	v_mfma_f32_32x32x16_bf16 v[34:49], v[76:79], v[102:105], v[34:49]
	ds_read_b128 v[76:79], v127 offset:20480
	v_exp_f32_e32 v175, v74
	v_pk_add_f32 v[66:67], v[166:167], v[66:67]
	v_exp_f32_e32 v181, v75
	v_pk_add_f32 v[66:67], v[172:173], v[66:67]
	v_cvt_pk_bf16_f32 v70, v129, v165
	v_pk_add_f32 v[66:67], v[170:171], v[66:67]
	s_waitcnt lgkmcnt(0)
	v_mfma_f32_32x32x16_bf16 v[34:49], v[76:79], v[98:101], v[34:49]
	ds_read_b128 v[76:79], v81 offset:24576
	v_cvt_pk_bf16_f32 v71, v163, v169
	v_cvt_pk_bf16_f32 v72, v167, v173
	v_cvt_pk_bf16_f32 v73, v171, v177
	v_add_f32_e64 v66, v176, v66
	v_add_f32_e64 v67, v177, v67
	v_cvt_pk_bf16_f32 v68, v183, v189
	v_pk_add_f32 v[66:67], v[174:175], v[66:67]
	s_waitcnt lgkmcnt(0)
	v_mfma_f32_32x32x16_bf16 v[18:33], v[76:79], v[102:105], v[18:33]
	ds_read_b128 v[76:79], v127 offset:24576
	v_add_f32_e64 v66, v180, v66
	v_add_f32_e64 v67, v181, v67
	v_cvt_pk_bf16_f32 v69, v187, v161
	v_add_f32_e64 v66, v178, v66
	v_add_f32_e64 v67, v179, v67
	v_pk_add_f32 v[66:67], v[184:185], v[66:67]
	s_waitcnt lgkmcnt(0)
	v_mfma_f32_32x32x16_bf16 v[18:33], v[76:79], v[98:101], v[18:33]
	ds_read_b128 v[76:79], v81 offset:28672
	v_add_u32_e32 v81, v80, v197
	v_add_u32_e32 v80, v80, v198
	v_add_f32_e64 v66, v182, v66
	v_add_f32_e64 v67, v183, v67
	v_pk_add_f32 v[66:67], v[188:189], v[66:67]
	s_waitcnt lgkmcnt(0)
	v_mfma_f32_32x32x16_bf16 v[2:17], v[76:79], v[102:105], v[2:17]
	ds_read_b128 v[76:79], v127 offset:28672
	v_add_f32_e64 v66, v186, v66
	v_add_f32_e64 v67, v187, v67
	v_add_f32_e64 v74, v160, v66
	v_add_f32_e64 v75, v161, v67
	v_cvt_pk_bf16_f32 v66, v175, v181
	v_cvt_pk_bf16_f32 v67, v179, v185
	v_add_f32_e32 v160, v74, v75
	s_waitcnt lgkmcnt(0)
	v_mfma_f32_32x32x16_bf16 v[2:17], v[76:79], v[98:101], v[2:17]
	ds_read_b128 v[76:79], v81 offset:16384
	s_waitcnt lgkmcnt(0)
	v_mfma_f32_32x32x16_bf16 v[50:65], v[76:79], v[70:73], v[50:65]
	ds_read_b128 v[76:79], v80 offset:16384
	s_waitcnt lgkmcnt(0)
	v_mfma_f32_32x32x16_bf16 v[50:65], v[76:79], v[66:69], v[50:65]
	ds_read_b128 v[76:79], v81 offset:20480
	s_waitcnt lgkmcnt(0)
	v_mfma_f32_32x32x16_bf16 v[34:49], v[76:79], v[70:73], v[34:49]
	ds_read_b128 v[76:79], v80 offset:20480
	s_waitcnt lgkmcnt(0)
	v_mfma_f32_32x32x16_bf16 v[34:49], v[76:79], v[66:69], v[34:49]
	ds_read_b128 v[76:79], v81 offset:24576
	s_waitcnt lgkmcnt(0)
	v_mfma_f32_32x32x16_bf16 v[18:33], v[76:79], v[70:73], v[18:33]
	ds_read_b128 v[76:79], v80 offset:24576
	s_waitcnt lgkmcnt(0)
	v_mfma_f32_32x32x16_bf16 v[18:33], v[76:79], v[66:69], v[18:33]
	ds_read_b128 v[76:79], v81 offset:28672
	s_waitcnt lgkmcnt(0)
	v_mfma_f32_32x32x16_bf16 v[2:17], v[76:79], v[70:73], v[2:17]
	ds_read_b128 v[70:73], v80 offset:28672
	s_waitcnt lgkmcnt(0)
	v_mfma_f32_32x32x16_bf16 v[2:17], v[70:73], v[66:69], v[2:17]
	v_mov_b32_e32 v66, v126
	s_andn2_b64 exec, exec, s[84:85]
	s_cbranch_execz .LBB0_237
